# static priority raise: s_setprio 2 for waves running S5 scan items (reset after), s_setprio 1 for waves 4-7 during the attention unit loop
# baseline (speedup 1.0000x reference)
; __device__ __forceinline__ void scan_item(unsigned char* ws, float* out, int l, int item, LAS unsigned char* wl, int lane_in) {
;     ...
;     int b, g, row0, nblk; const bool prompt = item < NB * 32;
;     if (prompt) { b = item >> 5; g = item & 31; row0 = b * SEQ; nblk = SEQ / 16; }
;     else { const int i2 = item - NB * 32; b = i2 >> 5; g = i2 & 31; row0 = TP + b * DSEQ; nblk = DSEQ / 16; }
.LBB0_444:
	s_setprio 2
	s_cmpk_gt_i32 s65, 0x3ff
	s_cselect_b64 s[58:59], -1, 0
	v_mov_b32_e32 v178, v234
	s_mov_b64 s[0:1], -1
	s_and_b64 vcc, exec, s[58:59]
	s_cbranch_vccz .LBB0_446
	s_add_i32 s0, s65, 0xfffffc00
	s_lshr_b32 s56, s0, 5
	s_lshl_b32 s0, s56, 6
	s_add_i32 s4, s0, 0x10000
	s_mov_b64 s[0:1], 0

; #define GAS __attribute__((address_space(1)))
; __device__ __forceinline__ void conv_run(unsigned char* ws, int l, int run, int lane_in) {
;     int lane = lane_in; asm volatile("" : "+v"(lane));
;     const GAS float* sm = (const GAS float*)(ws + WS_SMALL);
;     const bf16_t* XIN = (const bf16_t*)(ws + WS_XIN); const bf16_t* BG = (const bf16_t*)(ws + WS_BG); bf16_t* YCAT = (bf16_t*)(ws + WS_YCAT);
;     const int row0 = run * 64, c0 = lane * 8;
;     f32x4 w0a, w0b, w1a, w1b, w2a, w2b;
;     { const GAS float* cw = sm + SM_CONVW + (size_t)l * 3 * CH + c0; w0a = *(const GAS f32x4*)cw; w0b = *(const GAS f32x4*)(cw + 4); w1a = *(const GAS f32x4*)(cw + CH); w1b = *(const GAS f32x4*)(cw + CH + 4);
;       w2a = *(const GAS f32x4*)(cw + 2 * CH); w2b = *(const GAS f32x4*)(cw + 2 * CH + 4); }
; __global__ void __launch_bounds__(512, 2) hybrid_fwd(Args a) {
;     ...
;             for (int run = NGW2 - 1 - w; run < T / 64; run += NGW2) conv_run(wsp, ll, run, lane2);
.LBB0_513:
	s_setprio 0
	s_not_b32 s0, s18
	s_add_i32 s62, s83, s0
	v_readlane_b32 s96, v255, 38
	s_cmpk_gt_i32 s62, 0x40f
	v_readlane_b32 s97, v255, 39
	s_cbranch_scc1 .LBB0_524
	s_add_u32 s0, s86, 0x17500000
	s_addc_u32 s1, s87, 0
	s_add_u32 s2, s86, 0x13400000
	s_addc_u32 s3, s87, 0
	s_mul_i32 s5, s88, 0x1800
	s_mul_hi_i32 s4, s88, 0x1800
	s_add_u32 s5, s90, s5
	s_addc_u32 s4, s91, s4
	s_add_u32 s52, s5, 0x109100
	s_addc_u32 s53, s4, 0
	s_add_u32 s64, s90, 0x10c100
	s_addc_u32 s65, s91, 0
	s_lshl_b32 s69, s14, 9
	s_lshl_b32 s4, s18, 6
	s_sub_i32 s72, s69, s4
	v_readlane_b32 s4, v255, 18
	s_mul_i32 s4, s4, s14
	s_lshl_b32 s5, s15, 6
	s_lshl_b32 s68, s88, 4
	s_sub_i32 s73, s4, s5

; #define LAS __attribute__((address_space(3)))
; __device__ __forceinline__ void attn_phase(unsigned char* ws, int l, LAS unsigned char* lds, int G, int bid) {
;     int tid = threadIdx.x; asm volatile("" : "+v"(tid));
;     const int wave = __builtin_amdgcn_readfirstlane(tid >> 6);
;     const bf16_t* Q = (const bf16_t*)(ws + WS_Q); bf16_t* O = (bf16_t*)(ws + WS_O);
;     const int NU = NB * 4 * 8 + NDB * 4;
;     u32x4 kpre[16]; bool have = false;
; #pragma unroll
;     for (int i = 0; i < 16; ++i) kpre[i] = (u32x4){0u, 0u, 0u, 0u};
;     for (int u = bid; u < NU; u += G) {
;         int qrow0, nq, ldv; const bf16_t* Kp; const bf16_t* Vp; int h;
;         if (u < NB * 32) { const int b = u >> 5; h = (u >> 3) & 3; const int qt = u & 7; qrow0 = b * SEQ + qt * 256; nq = 256;
;             Kp = (const bf16_t*)(ws + WS_KB) + (size_t)l * TM * D + (size_t)(b * NMEM) * D + h * 256; Vp = (const bf16_t*)(ws + WS_VT) + (size_t)l * D * TM + (size_t)(h * 256) * TM + b * NMEM; ldv = TM; }
;         else { const int i = u - NB * 32, b = i >> 2; h = i & 3; qrow0 = TP + b * DSEQ; nq = DSEQ;
;             Kp = (const bf16_t*)(ws + WS_KC) + (size_t)l * TMS * D + (size_t)(b * NMEM) * D + h * 256; Vp = (const bf16_t*)(ws + WS_VTC) + (size_t)l * D * TMS + (size_t)(h * 256) * TMS + b * NMEM; ldv = TMS; }
;         const bool active = wave * 32 < nq;
.LBB0_866:
	s_or_b64 exec, exec, s[0:1]
	s_mov_b32 s4, s14
	s_mov_b32 s16, s90
	s_mov_b64 s[0:1], s[74:75]
	s_mov_b32 s17, s83
	v_mov_b32_e32 v195, v242
	s_waitcnt lgkmcnt(0)
	s_barrier
	s_cmpk_lt_i32 s17, 0x440
	s_nop 0
	v_readfirstlane_b32 s6, v195
	s_cbranch_scc0 .LBB0_891
	s_cmpk_lt_u32 s6, 0x100
	s_cbranch_scc1 .Lattn_prio_done
	s_setprio 1
.Lattn_prio_done:
	s_add_u32 s2, s0, 0x13400000
	s_addc_u32 s3, s1, 0
	s_add_u32 s52, s0, 0x1b600000
	s_addc_u32 s53, s1, 0
	s_ashr_i32 s5, s4, 31
	s_lshl_b64 s[8:9], s[4:5], 23
	s_add_u32 s7, s0, s8
	s_addc_u32 s8, s1, s9
	s_add_u32 s56, s7, 0x11400000
	s_addc_u32 s57, s8, 0
	s_add_u32 s58, s7, 0x12400000
	s_addc_u32 s59, s8, 0
	s_lshl_b64 s[4:5], s[4:5], 24
	s_add_u32 s0, s0, s4
	s_addc_u32 s1, s1, s5
	s_add_u32 s84, s0, 0xd400000
	s_addc_u32 s85, s1, 0
	s_add_u32 s86, s0, 0xf400000
	s_addc_u32 s87, s1, 0
	s_ashr_i32 s64, s6, 1
	s_add_i32 s0, s17, s16
	v_mov_b32_e32 v142, 0
	s_andn2_b32 s64, s64, 31
	s_lshl_b32 s65, s17, 8
	s_lshl_b32 s68, s16, 8
	s_lshl_b32 s69, s0, 6
	s_lshl_b32 s72, s16, 6
	s_lshl_b32 s73, s0, 3
	s_lshl_b32 s79, s16, 3
	s_mov_b64 s[0:1], 0
	v_mov_b32_e32 v143, v142
	v_mov_b32_e32 v144, v142
	v_mov_b32_e32 v145, v142
	v_mov_b32_e32 v118, v142
	v_mov_b32_e32 v119, v142
	v_mov_b32_e32 v120, v142
	v_mov_b32_e32 v121, v142
	v_mov_b32_e32 v122, v142
	v_mov_b32_e32 v123, v142
	v_mov_b32_e32 v124, v142
	v_mov_b32_e32 v125, v142
	v_mov_b32_e32 v126, v142
	v_mov_b32_e32 v127, v142
	v_mov_b32_e32 v128, v142
	v_mov_b32_e32 v129, v142
	v_mov_b32_e32 v134, v142
	v_mov_b32_e32 v135, v142
	v_mov_b32_e32 v136, v142
	v_mov_b32_e32 v137, v142
	v_mov_b32_e32 v138, v142
	v_mov_b32_e32 v139, v142
	v_mov_b32_e32 v140, v142
	v_mov_b32_e32 v141, v142
	v_mov_b32_e32 v150, v142
	v_mov_b32_e32 v151, v142
	v_mov_b32_e32 v152, v142
	v_mov_b32_e32 v153, v142
	v_mov_b32_e32 v158, v142
	v_mov_b32_e32 v159, v142
	v_mov_b32_e32 v160, v142
	v_mov_b32_e32 v161, v142
	v_mov_b32_e32 v162, v142
	v_mov_b32_e32 v163, v142
	v_mov_b32_e32 v164, v142
	v_mov_b32_e32 v165, v142
	v_mov_b32_e32 v166, v142
	v_mov_b32_e32 v167, v142
	v_mov_b32_e32 v168, v142
	v_mov_b32_e32 v169, v142
	v_mov_b32_e32 v170, v142
	v_mov_b32_e32 v171, v142
	v_mov_b32_e32 v172, v142
	v_mov_b32_e32 v173, v142
	v_mov_b32_e32 v174, v142
	v_mov_b32_e32 v175, v142
	v_mov_b32_e32 v176, v142
	v_mov_b32_e32 v177, v142
	v_mov_b32_e32 v178, v142
	v_mov_b32_e32 v179, v142
	v_mov_b32_e32 v180, v142
	v_mov_b32_e32 v181, v142
	s_waitcnt vmcnt(0)
	v_mov_b32_e32 v186, v142
	v_mov_b32_e32 v187, v142
	v_mov_b32_e32 v188, v142
	v_mov_b32_e32 v189, v142
	v_mov_b32_e32 v190, v142
	v_mov_b32_e32 v191, v142
	v_mov_b32_e32 v192, v142
	v_mov_b32_e32 v193, v142
	v_mov_b32_e32 v66, v142
	v_mov_b32_e32 v67, v142
	v_mov_b32_e32 v68, v142
	v_mov_b32_e32 v69, v142
	s_mov_b32 s13, 0x10000
	s_mov_b32 s14, 0x18000
	s_mov_b32 s15, 0x8000
	s_movk_i32 s18, 0x210
	s_mov_b32 s19, 0x40000
	s_mov_b32 s20, 0x20000
	s_mov_b32 s21, 0x28000
	s_mov_b32 s22, 0x30000
	s_mov_b32 s23, 0x38000
	s_mov_b32 s24, 0xff61b1e6
	s_branch .LBB0_869

; __device__ __forceinline__ void xcd_barrier(const XcdBarrier& b) {
;     asm volatile("s_waitcnt vmcnt(0)" ::: "memory");
;     __syncthreads();
;     if (threadIdx.x == 0) {
;         unsigned* bar = b.bar;
;         __builtin_amdgcn_s_waitcnt(0);
;         unsigned nloc = b.st[0], nx = b.st[1];
;         if (nloc == 0u) { xcd_barrier_complete(bar, b.x, nloc, nx); b.st[0] = nloc; b.st[1] = nx; }
.LBB0_891:
	s_setprio 0
	v_readlane_b32 s8, v255, 2
	s_barrier
	s_waitcnt vmcnt(0)
	s_barrier
	s_mov_b64 s[0:1], exec
	v_readlane_b32 s2, v255, 3
	v_readlane_b32 s3, v255, 4
	s_and_b64 s[2:3], s[0:1], s[2:3]
	s_xor_b64 s[0:1], s[2:3], s[0:1]
	s_mov_b64 exec, s[2:3]
	s_cbranch_execz .LBB0_944
	v_readlane_b32 s2, v255, 20
	s_waitcnt vmcnt(0) expcnt(0) lgkmcnt(0)
	s_nop 0
	v_mov_b32_e32 v0, s2
	ds_read_b32 v2, v0
	v_readlane_b32 s2, v255, 21
	s_waitcnt lgkmcnt(0)
	v_cmp_ne_u32_e32 vcc, 0, v2
	v_mov_b32_e32 v0, s2
	ds_read_b32 v0, v0
	s_cbranch_vccnz .LBB0_907
	s_mov_b32 s9, 1
	s_branch .LBB0_895
